# v23: v22 with both order splits (attention phase, sample-attention phase) on bid bit 0 (whole XCDs in the same sub-phase)
# speedup vs baseline: 1.0044x; 1.0044x over previous
.LBB0_1679:
	s_cmp_lt_i32 s96, 8
	s_cselect_b64 s[14:15], -1, 0
	s_and_b64 s[0:1], s[14:15], s[0:1]
	s_andn2_b64 vcc, exec, s[0:1]
	s_cbranch_vccnz .LBB0_1962
	s_mov_b32 s0, 0
	v_writelane_b32 v255, s0, 0
	s_bitcmp1_b32 s94, 0
	s_cbranch_scc0 .Lsattn_body
	v_writelane_b32 v255, s14, 1
	v_writelane_b32 v255, s15, 2
	v_writelane_b32 v255, s64, 3
	v_writelane_b32 v255, s65, 4
	v_writelane_b32 v255, s66, 5
	v_writelane_b32 v255, s67, 6
	v_writelane_b32 v255, s68, 7
	v_writelane_b32 v255, s69, 8
	v_writelane_b32 v255, s70, 9
	v_writelane_b32 v255, s71, 10
	v_writelane_b32 v255, s72, 11
	v_writelane_b32 v255, s73, 12
	v_writelane_b32 v255, s74, 13
	v_writelane_b32 v255, s75, 14
	v_writelane_b32 v255, s76, 15
	v_writelane_b32 v255, s77, 16
	v_writelane_b32 v255, s78, 17
	v_writelane_b32 v255, s79, 18
	s_branch .Lbr_body

.LBB0_1961:
	s_or_b64 exec, exec, s[2:3]
	s_waitcnt vmcnt(0) lgkmcnt(0)
	s_barrier
	s_bitcmp1_b32 s94, 0
	s_cbranch_scc1 .LBB0_1962
	v_writelane_b32 v255, s14, 1
	v_writelane_b32 v255, s15, 2
	v_writelane_b32 v255, s64, 3
	v_writelane_b32 v255, s65, 4
	v_writelane_b32 v255, s66, 5
	v_writelane_b32 v255, s67, 6
	v_writelane_b32 v255, s68, 7
	v_writelane_b32 v255, s69, 8
	v_writelane_b32 v255, s70, 9
	v_writelane_b32 v255, s71, 10
	v_writelane_b32 v255, s72, 11
	v_writelane_b32 v255, s73, 12
	v_writelane_b32 v255, s74, 13
	v_writelane_b32 v255, s75, 14
	v_writelane_b32 v255, s76, 15
	v_writelane_b32 v255, s77, 16
	v_writelane_b32 v255, s78, 17
	v_writelane_b32 v255, s79, 18
	s_branch .Lbr_body

.LBB0_2176:
	s_barrier
	v_readlane_b32 s0, v255, 0
	s_nop 0
	s_cmp_lg_u32 s0, 0
	s_cbranch_scc1 .LBB0_2177
	s_bitcmp1_b32 s94, 0
	s_cbranch_scc1 .Lbr_ret_a
	s_branch .Lbr_ret_b
